# on top of v32: G1 K loop - first two phases of every tile after the first run from a peeled copy whose counted waits tolerate the 16 epilogue stores still in flight (vmcnt 8 -> 24)
# speedup vs baseline: 1.0005x; 1.0005x over previous
.LBB0_150:
	s_cmp_lt_i32 s94, 2
	s_cselect_b64 s[0:1], -1, 0
	s_cmp_gt_i32 s95, 1
	s_cselect_b64 s[2:3], -1, 0
	s_and_b64 s[0:1], s[0:1], s[2:3]
	s_andn2_b64 vcc, exec, s[0:1]
	s_cbranch_vccnz .LBB0_343
	s_mov_b32 s99, 0
	s_mov_b64 s[0:1], s[76:77]
	s_load_dwordx2 s[10:11], s[0:1], 0xb0
	s_mov_b64 s[0:1], s[76:77]
	v_mov_b32_e32 v0, v216
	s_load_dword s0, s[76:77], 0xc0
	s_add_u32 s2, s76, 0xc0
	s_addc_u32 s3, s77, 0
	s_mov_b32 s33, s72
	s_waitcnt vmcnt(1)
	v_mov_b32_e32 v8, v216
	s_waitcnt lgkmcnt(0)
	s_mov_b32 s1, s0
	s_cmpk_lt_i32 s33, 0x13c0
	s_cselect_b64 s[4:5], -1, 0
	s_cmpk_gt_i32 s33, 0x13bf
	v_readfirstlane_b32 s26, v8
	s_cbranch_scc1 .LBB0_154
	s_ashr_i32 s6, s33, 31
	s_lshr_b32 s6, s6, 29
	s_add_i32 s6, s33, s6
	s_ashr_i32 s7, s6, 3
	s_and_b32 s6, s6, -8
	s_sub_i32 s6, s33, s6
	s_cmp_lt_i32 s6, 0
	s_movk_i32 s8, 0x279
	s_cselect_b32 s8, s8, 0x278
	s_mul_i32 s6, s8, s6
	s_add_i32 s6, s6, s7
	s_mul_hi_i32 s7, s6, 0x67b23a55
	s_lshr_b32 s8, s7, 31
	s_ashr_i32 s17, s7, 8
	s_add_i32 s17, s17, s8
	s_mul_i32 s7, s17, 0x278
	s_sub_i32 s6, s6, s7
	s_bfe_u32 s7, s6, 0x3001c
	s_add_i32 s7, s6, s7
	s_sext_i32_i16 s8, s7
	s_and_b32 s7, s7, 0xfff8
	s_lshr_b32 s16, s8, 3
	s_sub_i32 s18, s6, s7
	s_ashr_i32 s6, s8, 3
	s_cmp_lt_i32 s6, 30
	s_mov_b32 s7, 0
	s_cbranch_scc1 .LBB0_155
	s_sext_i32_i16 s12, s16
	s_cmp_gt_i32 s12, 33
	s_mov_b64 s[8:9], -1
	s_cselect_b64 s[12:13], -1, 0
	s_lshl_b32 s17, s17, 3
	s_sext_i32_i16 s14, s18
	s_cbranch_execz .LBB0_156
	s_branch .LBB0_157

.LBB0_179:
	s_add_u32 s12, s48, 0x100
	s_addc_u32 s39, s49, 0
	s_add_u32 s8, s8, 0x80080
	v_mov_b32_e32 v0, 0
	s_addc_u32 s9, s9, 0
	s_mov_b32 s68, -2
	s_waitcnt lgkmcnt(0)
	v_mov_b32_e32 v1, v0
	v_mov_b32_e32 v2, v0
	v_mov_b32_e32 v3, v0
	v_mov_b32_e32 v4, v0
	v_mov_b32_e32 v5, v0
	v_mov_b32_e32 v6, v0
	v_mov_b32_e32 v7, v0
	v_mov_b32_e32 v16, v0
	v_mov_b32_e32 v17, v0
	v_mov_b32_e32 v18, v0
	v_mov_b32_e32 v19, v0
	v_mov_b32_e32 v20, v0
	v_mov_b32_e32 v21, v0
	v_mov_b32_e32 v22, v0
	v_mov_b32_e32 v23, v0
	v_mov_b32_e32 v32, v0
	v_mov_b32_e32 v33, v0
	v_mov_b32_e32 v34, v0
	v_mov_b32_e32 v35, v0
	v_mov_b32_e32 v36, v0
	v_mov_b32_e32 v37, v0
	v_mov_b32_e32 v38, v0
	v_mov_b32_e32 v39, v0
	v_mov_b32_e32 v48, v0
	v_mov_b32_e32 v49, v0
	v_mov_b32_e32 v50, v0
	v_mov_b32_e32 v51, v0
	v_mov_b32_e32 v52, v0
	v_mov_b32_e32 v53, v0
	v_mov_b32_e32 v54, v0
	v_mov_b32_e32 v55, v0
	v_mov_b32_e32 v8, v0
	v_mov_b32_e32 v9, v0
	v_mov_b32_e32 v10, v0
	v_mov_b32_e32 v11, v0
	v_mov_b32_e32 v12, v0
	v_mov_b32_e32 v13, v0
	v_mov_b32_e32 v14, v0
	v_mov_b32_e32 v15, v0
	v_mov_b32_e32 v24, v0
	v_mov_b32_e32 v25, v0
	v_mov_b32_e32 v26, v0
	v_mov_b32_e32 v27, v0
	v_mov_b32_e32 v28, v0
	v_mov_b32_e32 v29, v0
	v_mov_b32_e32 v30, v0
	v_mov_b32_e32 v31, v0
	v_mov_b32_e32 v40, v0
	v_mov_b32_e32 v41, v0
	v_mov_b32_e32 v42, v0
	v_mov_b32_e32 v43, v0
	v_mov_b32_e32 v44, v0
	v_mov_b32_e32 v45, v0
	v_mov_b32_e32 v46, v0
	v_mov_b32_e32 v47, v0
	v_mov_b32_e32 v56, v0
	v_mov_b32_e32 v57, v0
	v_mov_b32_e32 v58, v0
	v_mov_b32_e32 v59, v0
	v_mov_b32_e32 v60, v0
	v_mov_b32_e32 v61, v0
	v_mov_b32_e32 v62, v0
	v_mov_b32_e32 v63, v0
	v_mov_b32_e32 v64, v0
	v_mov_b32_e32 v65, v0
	v_mov_b32_e32 v66, v0
	v_mov_b32_e32 v67, v0
	v_mov_b32_e32 v68, v0
	v_mov_b32_e32 v69, v0
	v_mov_b32_e32 v70, v0
	v_mov_b32_e32 v71, v0
	v_mov_b32_e32 v80, v0
	v_mov_b32_e32 v81, v0
	v_mov_b32_e32 v82, v0
	v_mov_b32_e32 v83, v0
	v_mov_b32_e32 v84, v0
	v_mov_b32_e32 v85, v0
	v_mov_b32_e32 v86, v0
	v_mov_b32_e32 v87, v0
	v_mov_b32_e32 v96, v0
	v_mov_b32_e32 v97, v0
	v_mov_b32_e32 v98, v0
	v_mov_b32_e32 v99, v0
	v_mov_b32_e32 v100, v0
	v_mov_b32_e32 v101, v0
	v_mov_b32_e32 v102, v0
	v_mov_b32_e32 v103, v0
	v_mov_b32_e32 v112, v0
	v_mov_b32_e32 v113, v0
	v_mov_b32_e32 v114, v0
	v_mov_b32_e32 v115, v0
	v_mov_b32_e32 v116, v0
	v_mov_b32_e32 v117, v0
	v_mov_b32_e32 v118, v0
	v_mov_b32_e32 v119, v0
	v_mov_b32_e32 v72, v0
	v_mov_b32_e32 v73, v0
	v_mov_b32_e32 v74, v0
	v_mov_b32_e32 v75, v0
	v_mov_b32_e32 v76, v0
	v_mov_b32_e32 v77, v0
	v_mov_b32_e32 v78, v0
	v_mov_b32_e32 v79, v0
	v_mov_b32_e32 v88, v0
	v_mov_b32_e32 v89, v0
	v_mov_b32_e32 v90, v0
	v_mov_b32_e32 v91, v0
	v_mov_b32_e32 v92, v0
	v_mov_b32_e32 v93, v0
	v_mov_b32_e32 v94, v0
	v_mov_b32_e32 v95, v0
	v_mov_b32_e32 v104, v0
	v_mov_b32_e32 v105, v0
	v_mov_b32_e32 v106, v0
	v_mov_b32_e32 v107, v0
	v_mov_b32_e32 v108, v0
	v_mov_b32_e32 v109, v0
	v_mov_b32_e32 v110, v0
	v_mov_b32_e32 v111, v0
	v_mov_b32_e32 v120, v0
	v_mov_b32_e32 v121, v0
	v_mov_b32_e32 v122, v0
	v_mov_b32_e32 v123, v0
	v_mov_b32_e32 v124, v0
	v_mov_b32_e32 v125, v0
	v_mov_b32_e32 v126, v0
	v_mov_b32_e32 v127, v0
	s_cmp_eq_u32 s99, 0
	s_cbranch_scc1 .LBB0_180
	ds_read_b128 v[152:155], v170
	ds_read_b128 v[156:159], v170 offset:1024
	ds_read_b128 v[174:177], v170 offset:2048
	ds_read_b128 v[178:181], v170 offset:3072
	ds_read_b128 v[182:185], v171
	ds_read_b128 v[186:189], v171 offset:1024
	ds_read_b128 v[190:193], v171 offset:2048
	ds_read_b128 v[194:197], v171 offset:3072
	s_add_u32 s48, s8, 0xfff80080
	s_addc_u32 s49, s9, -1
	s_cmp_eq_u32 s68, 28
	s_cselect_b32 s51, s41, s49
	s_cselect_b32 s50, s40, s48
	s_cselect_b32 s49, s43, s39
	s_cselect_b32 s48, s42, s12
	v_lshl_add_u64 v[160:161], s[8:9], 0, v[146:147]
	s_add_i32 m0, s52, 0xc000
	ds_read_b128 v[198:201], v172
	ds_read_b128 v[202:205], v172 offset:1024
	ds_read_b128 v[206:209], v172 offset:2048
	ds_read_b128 v[210:213], v172 offset:3072
	ds_read_b128 v[218:221], v172 offset:4096
	ds_read_b128 v[222:225], v172 offset:5120
	ds_read_b128 v[226:229], v172 offset:6144
	ds_read_b128 v[230:233], v172 offset:7168
	global_load_lds_dwordx4 v[160:161], off
	v_lshl_add_u64 v[160:161], s[8:9], 0, v[144:145]
	s_add_i32 m0, s52, 0xe000
	s_nop 0
	global_load_lds_dwordx4 v[160:161], off
	s_waitcnt vmcnt(24)
	s_waitcnt lgkmcnt(0)
	s_barrier
	s_setprio 1
	s_waitcnt lgkmcnt(0)
	v_mfma_f32_16x16x32_bf16 v[124:127], v[152:155], v[198:201], v[124:127]
	v_mfma_f32_16x16x32_bf16 v[120:123], v[174:177], v[198:201], v[120:123]
	v_mfma_f32_16x16x32_bf16 v[108:111], v[152:155], v[206:209], v[108:111]
	v_mfma_f32_16x16x32_bf16 v[104:107], v[174:177], v[206:209], v[104:107]
	v_mfma_f32_16x16x32_bf16 v[92:95], v[152:155], v[218:221], v[92:95]
	v_mfma_f32_16x16x32_bf16 v[88:91], v[174:177], v[218:221], v[88:91]
	v_mfma_f32_16x16x32_bf16 v[76:79], v[152:155], v[226:229], v[76:79]
	v_mfma_f32_16x16x32_bf16 v[72:75], v[174:177], v[226:229], v[72:75]
	v_mfma_f32_16x16x32_bf16 v[124:127], v[156:159], v[202:205], v[124:127]
	v_mfma_f32_16x16x32_bf16 v[120:123], v[178:181], v[202:205], v[120:123]
	v_mfma_f32_16x16x32_bf16 v[108:111], v[156:159], v[210:213], v[108:111]
	v_mfma_f32_16x16x32_bf16 v[104:107], v[178:181], v[210:213], v[104:107]
	v_mfma_f32_16x16x32_bf16 v[92:95], v[156:159], v[222:225], v[92:95]
	v_mfma_f32_16x16x32_bf16 v[88:91], v[178:181], v[222:225], v[88:91]
	v_mfma_f32_16x16x32_bf16 v[76:79], v[156:159], v[230:233], v[76:79]
	v_mfma_f32_16x16x32_bf16 v[72:75], v[178:181], v[230:233], v[72:75]
	s_setprio 0
	s_setprio 1
	v_mfma_f32_16x16x32_bf16 v[116:119], v[182:185], v[198:201], v[116:119]
	v_mfma_f32_16x16x32_bf16 v[112:115], v[190:193], v[198:201], v[112:115]
	v_mfma_f32_16x16x32_bf16 v[100:103], v[182:185], v[206:209], v[100:103]
	v_mfma_f32_16x16x32_bf16 v[96:99], v[190:193], v[206:209], v[96:99]
	v_mfma_f32_16x16x32_bf16 v[84:87], v[182:185], v[218:221], v[84:87]
	v_mfma_f32_16x16x32_bf16 v[80:83], v[190:193], v[218:221], v[80:83]
	v_mfma_f32_16x16x32_bf16 v[68:71], v[182:185], v[226:229], v[68:71]
	v_mfma_f32_16x16x32_bf16 v[64:67], v[190:193], v[226:229], v[64:67]
	v_mfma_f32_16x16x32_bf16 v[116:119], v[186:189], v[202:205], v[116:119]
	v_mfma_f32_16x16x32_bf16 v[112:115], v[194:197], v[202:205], v[112:115]
	v_mfma_f32_16x16x32_bf16 v[100:103], v[186:189], v[210:213], v[100:103]
	v_mfma_f32_16x16x32_bf16 v[96:99], v[194:197], v[210:213], v[96:99]
	v_mfma_f32_16x16x32_bf16 v[84:87], v[186:189], v[222:225], v[84:87]
	v_mfma_f32_16x16x32_bf16 v[80:83], v[194:197], v[222:225], v[80:83]
	v_mfma_f32_16x16x32_bf16 v[68:71], v[186:189], v[230:233], v[68:71]
	v_mfma_f32_16x16x32_bf16 v[64:67], v[194:197], v[230:233], v[64:67]
	s_setprio 0
	s_barrier
	s_add_i32 s69, s64, s47
	v_lshl_add_u64 v[160:161], s[48:49], 0, v[130:131]
	s_mov_b32 m0, s69
	ds_read_b128 v[198:201], v172 offset:16384
	ds_read_b128 v[202:205], v172 offset:17408
	ds_read_b128 v[206:209], v172 offset:18432
	ds_read_b128 v[210:213], v172 offset:19456
	ds_read_b128 v[218:221], v172 offset:20480
	ds_read_b128 v[222:225], v172 offset:21504
	ds_read_b128 v[226:229], v172 offset:22528
	ds_read_b128 v[230:233], v172 offset:23552
	global_load_lds_dwordx4 v[160:161], off
	s_add_i32 m0, s69, 0x2000
	s_add_u32 s70, s48, 0x80000
	v_lshl_add_u64 v[214:215], s[48:49], 0, v[134:135]
	s_addc_u32 s71, s49, 0
	s_add_i32 s69, s65, s47
	global_load_lds_dwordx4 v[214:215], off
	v_lshl_add_u64 v[234:235], s[70:71], 0, v[130:131]
	s_mov_b32 m0, s69
	v_lshl_add_u64 v[236:237], s[50:51], 0, v[132:133]
	global_load_lds_dwordx4 v[234:235], off
	v_lshl_add_u64 v[234:235], s[70:71], 0, v[134:135]
	s_add_i32 m0, s69, 0x2000
	s_nop 0
	global_load_lds_dwordx4 v[234:235], off
	v_lshl_add_u64 v[234:235], s[50:51], 0, v[128:129]
	s_mov_b32 m0, s52
	s_nop 0
	global_load_lds_dwordx4 v[234:235], off
	s_mov_b32 m0, s53
	s_nop 0
	global_load_lds_dwordx4 v[236:237], off
	s_waitcnt vmcnt(24)
	s_waitcnt lgkmcnt(0)
	s_barrier
	s_setprio 1
	s_waitcnt lgkmcnt(0)
	v_mfma_f32_16x16x32_bf16 v[60:63], v[152:155], v[198:201], v[60:63]
	v_mfma_f32_16x16x32_bf16 v[56:59], v[174:177], v[198:201], v[56:59]
	v_mfma_f32_16x16x32_bf16 v[44:47], v[152:155], v[206:209], v[44:47]
	v_mfma_f32_16x16x32_bf16 v[40:43], v[174:177], v[206:209], v[40:43]
	v_mfma_f32_16x16x32_bf16 v[28:31], v[152:155], v[218:221], v[28:31]
	v_mfma_f32_16x16x32_bf16 v[24:27], v[174:177], v[218:221], v[24:27]
	v_mfma_f32_16x16x32_bf16 v[12:15], v[152:155], v[226:229], v[12:15]
	v_mfma_f32_16x16x32_bf16 v[8:11], v[174:177], v[226:229], v[8:11]
	v_mfma_f32_16x16x32_bf16 v[60:63], v[156:159], v[202:205], v[60:63]
	v_mfma_f32_16x16x32_bf16 v[56:59], v[178:181], v[202:205], v[56:59]
	v_mfma_f32_16x16x32_bf16 v[44:47], v[156:159], v[210:213], v[44:47]
	v_mfma_f32_16x16x32_bf16 v[40:43], v[178:181], v[210:213], v[40:43]
	v_mfma_f32_16x16x32_bf16 v[28:31], v[156:159], v[222:225], v[28:31]
	v_mfma_f32_16x16x32_bf16 v[24:27], v[178:181], v[222:225], v[24:27]
	v_mfma_f32_16x16x32_bf16 v[12:15], v[156:159], v[230:233], v[12:15]
	v_mfma_f32_16x16x32_bf16 v[8:11], v[178:181], v[230:233], v[8:11]
	s_setprio 0
	s_setprio 1
	v_mfma_f32_16x16x32_bf16 v[52:55], v[182:185], v[198:201], v[52:55]
	v_mfma_f32_16x16x32_bf16 v[48:51], v[190:193], v[198:201], v[48:51]
	v_mfma_f32_16x16x32_bf16 v[36:39], v[182:185], v[206:209], v[36:39]
	v_mfma_f32_16x16x32_bf16 v[32:35], v[190:193], v[206:209], v[32:35]
	v_mfma_f32_16x16x32_bf16 v[20:23], v[182:185], v[218:221], v[20:23]
	v_mfma_f32_16x16x32_bf16 v[16:19], v[190:193], v[218:221], v[16:19]
	v_mfma_f32_16x16x32_bf16 v[4:7], v[182:185], v[226:229], v[4:7]
	v_mfma_f32_16x16x32_bf16 v[0:3], v[190:193], v[226:229], v[0:3]
	v_mfma_f32_16x16x32_bf16 v[52:55], v[186:189], v[202:205], v[52:55]
	v_mfma_f32_16x16x32_bf16 v[48:51], v[194:197], v[202:205], v[48:51]
	v_mfma_f32_16x16x32_bf16 v[36:39], v[186:189], v[210:213], v[36:39]
	v_mfma_f32_16x16x32_bf16 v[32:35], v[194:197], v[210:213], v[32:35]
	v_mfma_f32_16x16x32_bf16 v[20:23], v[186:189], v[222:225], v[20:23]
	v_mfma_f32_16x16x32_bf16 v[16:19], v[194:197], v[222:225], v[16:19]
	v_mfma_f32_16x16x32_bf16 v[4:7], v[186:189], v[230:233], v[4:7]
	v_mfma_f32_16x16x32_bf16 v[0:3], v[194:197], v[230:233], v[0:3]
	s_setprio 0
	s_barrier
	s_branch .Lpeel_mid_0

.Lpeel_mid_0:
	s_add_i32 s69, 0, 0x18000
	v_add_u32_e32 v136, s69, v141
	s_add_i32 s70, 0, 0x1c000
	ds_read_b128 v[152:155], v136
	ds_read_b128 v[156:159], v136 offset:1024
	ds_read_b128 v[174:177], v136 offset:2048
	ds_read_b128 v[178:181], v136 offset:3072
	v_add_u32_e32 v136, s70, v141
	ds_read_b128 v[182:185], v136
	ds_read_b128 v[186:189], v136 offset:1024
	ds_read_b128 v[190:193], v136 offset:2048
	ds_read_b128 v[194:197], v136 offset:3072
	s_add_u32 s50, s50, 0x80000
	s_addc_u32 s51, s51, 0
	s_mov_b32 m0, s54
	v_lshl_add_u64 v[238:239], s[50:51], 0, v[128:129]
	ds_read_b128 v[198:201], v172 offset:32768
	ds_read_b128 v[202:205], v172 offset:33792
	ds_read_b128 v[206:209], v172 offset:34816
	ds_read_b128 v[210:213], v172 offset:35840
	ds_read_b128 v[218:221], v172 offset:36864
	ds_read_b128 v[222:225], v172 offset:37888
	ds_read_b128 v[226:229], v172 offset:38912
	ds_read_b128 v[230:233], v172 offset:39936
	global_load_lds_dwordx4 v[238:239], off
	v_lshl_add_u64 v[238:239], s[50:51], 0, v[132:133]
	s_mov_b32 m0, s55
	s_nop 0
	global_load_lds_dwordx4 v[238:239], off
	s_waitcnt vmcnt(8)
	s_waitcnt lgkmcnt(0)
	s_barrier
	s_setprio 1
	s_waitcnt lgkmcnt(0)
	v_mfma_f32_16x16x32_bf16 v[124:127], v[152:155], v[198:201], v[124:127]
	v_mfma_f32_16x16x32_bf16 v[120:123], v[174:177], v[198:201], v[120:123]
	v_mfma_f32_16x16x32_bf16 v[108:111], v[152:155], v[206:209], v[108:111]
	v_mfma_f32_16x16x32_bf16 v[104:107], v[174:177], v[206:209], v[104:107]
	v_mfma_f32_16x16x32_bf16 v[92:95], v[152:155], v[218:221], v[92:95]
	v_mfma_f32_16x16x32_bf16 v[88:91], v[174:177], v[218:221], v[88:91]
	v_mfma_f32_16x16x32_bf16 v[76:79], v[152:155], v[226:229], v[76:79]
	v_mfma_f32_16x16x32_bf16 v[72:75], v[174:177], v[226:229], v[72:75]
	v_mfma_f32_16x16x32_bf16 v[124:127], v[156:159], v[202:205], v[124:127]
	v_mfma_f32_16x16x32_bf16 v[120:123], v[178:181], v[202:205], v[120:123]
	v_mfma_f32_16x16x32_bf16 v[108:111], v[156:159], v[210:213], v[108:111]
	v_mfma_f32_16x16x32_bf16 v[104:107], v[178:181], v[210:213], v[104:107]
	v_mfma_f32_16x16x32_bf16 v[92:95], v[156:159], v[222:225], v[92:95]
	v_mfma_f32_16x16x32_bf16 v[88:91], v[178:181], v[222:225], v[88:91]
	v_mfma_f32_16x16x32_bf16 v[76:79], v[156:159], v[230:233], v[76:79]
	v_mfma_f32_16x16x32_bf16 v[72:75], v[178:181], v[230:233], v[72:75]
	s_setprio 0
	s_setprio 1
	v_mfma_f32_16x16x32_bf16 v[116:119], v[182:185], v[198:201], v[116:119]
	v_mfma_f32_16x16x32_bf16 v[112:115], v[190:193], v[198:201], v[112:115]
	v_mfma_f32_16x16x32_bf16 v[100:103], v[182:185], v[206:209], v[100:103]
	v_mfma_f32_16x16x32_bf16 v[96:99], v[190:193], v[206:209], v[96:99]
	v_mfma_f32_16x16x32_bf16 v[84:87], v[182:185], v[218:221], v[84:87]
	v_mfma_f32_16x16x32_bf16 v[80:83], v[190:193], v[218:221], v[80:83]
	v_mfma_f32_16x16x32_bf16 v[68:71], v[182:185], v[226:229], v[68:71]
	v_mfma_f32_16x16x32_bf16 v[64:67], v[190:193], v[226:229], v[64:67]
	v_mfma_f32_16x16x32_bf16 v[116:119], v[186:189], v[202:205], v[116:119]
	v_mfma_f32_16x16x32_bf16 v[112:115], v[194:197], v[202:205], v[112:115]
	v_mfma_f32_16x16x32_bf16 v[100:103], v[186:189], v[210:213], v[100:103]
	v_mfma_f32_16x16x32_bf16 v[96:99], v[194:197], v[210:213], v[96:99]
	v_mfma_f32_16x16x32_bf16 v[84:87], v[186:189], v[222:225], v[84:87]
	v_mfma_f32_16x16x32_bf16 v[80:83], v[194:197], v[222:225], v[80:83]
	v_mfma_f32_16x16x32_bf16 v[68:71], v[186:189], v[230:233], v[68:71]
	v_mfma_f32_16x16x32_bf16 v[64:67], v[194:197], v[230:233], v[64:67]
	s_setprio 0
	s_barrier
	s_add_i32 s50, s69, s47
	v_lshl_add_u64 v[160:161], v[160:161], 0, s[24:25]
	s_mov_b32 m0, s50
	ds_read_b128 v[198:201], v172 offset:49152
	ds_read_b128 v[202:205], v172 offset:50176
	ds_read_b128 v[206:209], v172 offset:51200
	ds_read_b128 v[210:213], v172 offset:52224
	ds_read_b128 v[218:221], v172 offset:53248
	ds_read_b128 v[222:225], v172 offset:54272
	ds_read_b128 v[226:229], v172 offset:55296
	ds_read_b128 v[230:233], v172 offset:56320
	global_load_lds_dwordx4 v[160:161], off
	s_add_i32 m0, s50, 0x2000
	s_add_u32 s48, s48, 0x80080
	v_lshl_add_u64 v[160:161], v[214:215], 0, s[24:25]
	s_addc_u32 s49, s49, 0
	s_add_i32 s50, s70, s47
	global_load_lds_dwordx4 v[160:161], off
	v_lshl_add_u64 v[160:161], s[48:49], 0, v[130:131]
	s_mov_b32 m0, s50
	s_nop 0
	global_load_lds_dwordx4 v[160:161], off
	v_lshl_add_u64 v[160:161], s[48:49], 0, v[134:135]
	s_add_i32 m0, s50, 0x2000
	s_nop 0
	global_load_lds_dwordx4 v[160:161], off
	v_lshl_add_u64 v[160:161], v[234:235], 0, s[24:25]
	s_mov_b32 m0, s59
	s_nop 0
	global_load_lds_dwordx4 v[160:161], off
	v_lshl_add_u64 v[160:161], v[236:237], 0, s[24:25]
	s_mov_b32 m0, s60
	s_nop 0
	global_load_lds_dwordx4 v[160:161], off
	s_waitcnt vmcnt(8)
	s_waitcnt lgkmcnt(0)
	s_barrier
	s_setprio 1
	s_waitcnt lgkmcnt(0)
	v_mfma_f32_16x16x32_bf16 v[60:63], v[152:155], v[198:201], v[60:63]
	v_mfma_f32_16x16x32_bf16 v[56:59], v[174:177], v[198:201], v[56:59]
	v_mfma_f32_16x16x32_bf16 v[44:47], v[152:155], v[206:209], v[44:47]
	v_mfma_f32_16x16x32_bf16 v[40:43], v[174:177], v[206:209], v[40:43]
	v_mfma_f32_16x16x32_bf16 v[28:31], v[152:155], v[218:221], v[28:31]
	v_mfma_f32_16x16x32_bf16 v[24:27], v[174:177], v[218:221], v[24:27]
	v_mfma_f32_16x16x32_bf16 v[12:15], v[152:155], v[226:229], v[12:15]
	v_mfma_f32_16x16x32_bf16 v[8:11], v[174:177], v[226:229], v[8:11]
	v_mfma_f32_16x16x32_bf16 v[60:63], v[156:159], v[202:205], v[60:63]
	v_mfma_f32_16x16x32_bf16 v[56:59], v[178:181], v[202:205], v[56:59]
	v_mfma_f32_16x16x32_bf16 v[44:47], v[156:159], v[210:213], v[44:47]
	v_mfma_f32_16x16x32_bf16 v[40:43], v[178:181], v[210:213], v[40:43]
	v_mfma_f32_16x16x32_bf16 v[28:31], v[156:159], v[222:225], v[28:31]
	v_mfma_f32_16x16x32_bf16 v[24:27], v[178:181], v[222:225], v[24:27]
	v_mfma_f32_16x16x32_bf16 v[12:15], v[156:159], v[230:233], v[12:15]
	v_mfma_f32_16x16x32_bf16 v[8:11], v[178:181], v[230:233], v[8:11]
	s_setprio 0
	s_setprio 1
	v_mfma_f32_16x16x32_bf16 v[52:55], v[182:185], v[198:201], v[52:55]
	v_mfma_f32_16x16x32_bf16 v[48:51], v[190:193], v[198:201], v[48:51]
	v_mfma_f32_16x16x32_bf16 v[36:39], v[182:185], v[206:209], v[36:39]
	v_mfma_f32_16x16x32_bf16 v[32:35], v[190:193], v[206:209], v[32:35]
	v_mfma_f32_16x16x32_bf16 v[20:23], v[182:185], v[218:221], v[20:23]
	v_mfma_f32_16x16x32_bf16 v[16:19], v[190:193], v[218:221], v[16:19]
	v_mfma_f32_16x16x32_bf16 v[4:7], v[182:185], v[226:229], v[4:7]
	v_mfma_f32_16x16x32_bf16 v[0:3], v[190:193], v[226:229], v[0:3]
	v_mfma_f32_16x16x32_bf16 v[52:55], v[186:189], v[202:205], v[52:55]
	v_mfma_f32_16x16x32_bf16 v[48:51], v[194:197], v[202:205], v[48:51]
	v_mfma_f32_16x16x32_bf16 v[36:39], v[186:189], v[210:213], v[36:39]
	v_mfma_f32_16x16x32_bf16 v[32:35], v[194:197], v[210:213], v[32:35]
	v_mfma_f32_16x16x32_bf16 v[20:23], v[186:189], v[222:225], v[20:23]
	v_mfma_f32_16x16x32_bf16 v[16:19], v[194:197], v[222:225], v[16:19]
	v_mfma_f32_16x16x32_bf16 v[4:7], v[186:189], v[230:233], v[4:7]
	v_mfma_f32_16x16x32_bf16 v[0:3], v[194:197], v[230:233], v[0:3]
	s_setprio 0
	s_barrier
	s_add_i32 s68, s68, 2
	s_add_u32 s12, s12, 0x100
	s_addc_u32 s39, s39, 0
	s_add_u32 s8, s8, 0x100
	s_addc_u32 s9, s9, 0
	s_cmp_gt_u32 s68, 29
	s_cbranch_scc0 .LBB0_180
	s_and_b64 vcc, exec, s[26:27]
	s_cbranch_vccz .LBB0_183
	s_barrier

.LBB0_289:
	s_mov_b32 s99, 1
	s_andn2_b64 vcc, exec, s[6:7]
	s_mov_b64 s[6:7], -1
	s_cbranch_vccnz .LBB0_167
	s_andn2_b64 vcc, exec, s[14:15]
	s_cbranch_vccnz .LBB0_166
	s_barrier
	s_branch .LBB0_166

.LBB0_1205:
	s_cmp_lt_i32 s94, 10
	s_cselect_b64 s[0:1], -1, 0
	s_cmp_gt_i32 s95, 9
	s_cselect_b64 s[2:3], -1, 0
	s_and_b64 s[0:1], s[0:1], s[2:3]
	s_andn2_b64 vcc, exec, s[0:1]
	s_cbranch_vccnz .LBB0_1398
	s_mov_b32 s99, 0
	s_mov_b64 s[0:1], s[76:77]
	s_load_dwordx2 s[10:11], s[0:1], 0xb0
	s_mov_b64 s[0:1], s[76:77]
	s_waitcnt vmcnt(0)
	v_mov_b32_e32 v0, v216
	s_load_dword s0, s[76:77], 0xc0
	s_add_u32 s2, s76, 0xc0
	s_addc_u32 s3, s77, 0
	s_mov_b32 s33, s72
	v_mov_b32_e32 v8, v216
	s_waitcnt lgkmcnt(0)
	s_mov_b32 s1, s0
	s_cmpk_lt_i32 s33, 0x13c0
	s_cselect_b64 s[4:5], -1, 0
	s_cmpk_gt_i32 s33, 0x13bf
	v_readfirstlane_b32 s26, v8
	s_cbranch_scc1 .LBB0_1209
	s_ashr_i32 s6, s33, 31
	s_lshr_b32 s6, s6, 29
	s_add_i32 s6, s33, s6
	s_ashr_i32 s7, s6, 3
	s_and_b32 s6, s6, -8
	s_sub_i32 s6, s33, s6
	s_cmp_lt_i32 s6, 0
	s_movk_i32 s8, 0x279
	s_cselect_b32 s8, s8, 0x278
	s_mul_i32 s6, s8, s6
	s_add_i32 s6, s6, s7
	s_mul_hi_i32 s7, s6, 0x67b23a55
	s_lshr_b32 s8, s7, 31
	s_ashr_i32 s17, s7, 8
	s_add_i32 s17, s17, s8
	s_mul_i32 s7, s17, 0x278
	s_sub_i32 s6, s6, s7
	s_bfe_u32 s7, s6, 0x3001c
	s_add_i32 s7, s6, s7
	s_sext_i32_i16 s8, s7
	s_and_b32 s7, s7, 0xfff8
	s_lshr_b32 s16, s8, 3
	s_sub_i32 s18, s6, s7
	s_ashr_i32 s6, s8, 3
	s_cmp_lt_i32 s6, 30
	s_mov_b32 s7, 0
	s_cbranch_scc1 .LBB0_1210
	s_sext_i32_i16 s12, s16
	s_cmp_gt_i32 s12, 33
	s_mov_b64 s[8:9], -1
	s_cselect_b64 s[12:13], -1, 0
	s_lshl_b32 s17, s17, 3
	s_sext_i32_i16 s14, s18
	s_cbranch_execz .LBB0_1211
	s_branch .LBB0_1212
